# weight conversion tiles (prologue + both deferred loops): both passes and gains loaded in one round trip
# speedup vs baseline: 1.0036x; 1.0036x over previous
.LBB0_17:
	s_lshl_b32 s0, s13, 7
	s_and_b32 s1, s14, 64
	s_and_b32 s0, s0, 0xffffff00
	s_or_b32 s1, s1, s18
	s_or_b32 s8, s1, s0
	s_and_b64 s[0:1], s[4:5], exec
	v_ashrrev_i32_e32 v12, 3, v3
	v_lshlrev_b32_e32 v3, 5, v3
	s_cselect_b32 s0, s14, s8
	v_and_b32_e32 v136, 0xe0, v3
	v_add_u32_e32 v3, s0, v12
	v_mul_lo_u32 v13, v12, s76
	v_ashrrev_i32_e32 v15, 31, v3
	v_add3_u32 v14, 0, v13, v136
	v_mul_lo_u32 v16, s7, v3
	v_mad_u64_u32 v[12:13], s[0:1], s6, v3, 0
	v_mul_lo_u32 v3, s6, v15
	v_add3_u32 v13, v13, v3, v16
	s_ashr_i32 s13, s12, 31
	s_add_i32 s17, s17, s98
	s_cmpk_lt_i32 s17, 0x620
	s_waitcnt lgkmcnt(0)
	s_barrier
	ds_read2_b32 v[0:1], v14 offset1:1
	ds_read2_b32 v[2:3], v14 offset0:2 offset1:3
	ds_read2_b32 v[4:5], v14 offset0:4 offset1:5
	ds_read2_b32 v[6:7], v14 offset0:6 offset1:7
	v_lshl_add_u64 v[8:9], v[12:13], 1, s[2:3]
	v_lshl_add_u64 v[8:9], s[12:13], 1, v[8:9]
	v_lshl_add_u64 v[8:9], v[8:9], 0, v[136:137]
	s_waitcnt lgkmcnt(2)
	global_store_dwordx4 v[8:9], v[0:3], off
	s_waitcnt lgkmcnt(0)
	global_store_dwordx4 v[8:9], v[4:7], off offset:16
	s_barrier
	s_cbranch_scc0 .LBB0_14

.LBB0_43:
	s_mul_i32 s0, s14, 0xba3
	s_lshr_b32 s1, s0, 31
	s_lshr_b32 s0, s0, 20
	s_lshr_b32 s19, s34, 6
	s_add_i32 s0, s0, s1
	v_cvt_f32_i32_e32 v0, s19
	s_mulk_i32 s0, 0x160
	s_sub_i32 s13, s14, s0
	s_sext_i32_i16 s0, s13
	v_cvt_f32_i32_e32 v1, s0
	v_rcp_iflag_f32_e32 v2, v0
	s_ashr_i32 s0, s0, 30
	s_or_b32 s12, s0, 1
	v_mov_b32_e32 v3, v147
	v_mul_f32_e32 v2, v1, v2
	v_trunc_f32_e32 v2, v2
	v_fma_f32 v1, -v2, v0, v1
	v_cvt_i32_f32_e32 v2, v2
	v_cmp_ge_f32_e64 s[0:1], |v1|, v0
	s_and_b64 s[0:1], s[0:1], exec
	s_cselect_b32 s0, s12, 0
	v_readfirstlane_b32 s1, v2
	s_add_i32 s1, s1, s0
	s_bfe_i32 s20, s1, 0xa0000
	s_lshl_b32 s12, s20, 7
	s_waitcnt lgkmcnt(0)
	v_ashrrev_i32_e32 v7, 4, v3
	v_lshl_add_u32 v0, v7, 1, s12
	v_ashrrev_i32_e32 v1, 31, v0
	v_mov_b32_e32 v20, 1.0
	v_mov_b32_e32 v22, 1.0
	v_mov_b32_e32 v40, 1.0
	v_mov_b32_e32 v42, 1.0
	s_cmp_eq_u64 s[10:11], 0
	s_cbranch_scc1 .Lwt0_nogain
	v_lshl_add_u64 v[4:5], v[0:1], 2, s[10:11]
	global_load_dword v20, v[4:5], off
	global_load_dword v22, v[4:5], off offset:4
	global_load_dword v40, v[4:5], off offset:256
	global_load_dword v42, v[4:5], off offset:260
.Lwt0_nogain:
	s_mul_i32 s20, s20, s19
	s_sub_i32 s13, s13, s20
	s_sext_i32_i16 s13, s13
	s_lshl_b32 s14, s13, 6
	s_ashr_i32 s15, s14, 31
	v_lshlrev_b32_e32 v4, 2, v3
	s_lshl_b64 s[20:21], s[14:15], 2
	v_and_b32_e32 v10, 60, v4
	s_add_u32 s8, s8, s20
	s_addc_u32 s9, s9, s21
	v_lshlrev_b32_e32 v136, 2, v10
	v_lshl_add_u64 v[4:5], s[8:9], 0, v[136:137]
	v_mad_u64_u32 v[8:9], s[8:9], v0, s34, 0
	v_mov_b32_e32 v0, v9
	v_mad_u64_u32 v[0:1], s[8:9], v1, s34, v[0:1]
	v_mov_b32_e32 v9, v0
	v_lshl_add_u64 v[0:1], v[8:9], 2, v[4:5]
	global_load_dwordx4 v[24:27], v[0:1], off
	v_lshl_add_u64 v[12:13], s[34:35], 2, v[0:1]
	global_load_dwordx4 v[28:31], v[12:13], off
	s_lshl_b32 s0, s34, 8
	s_mov_b32 s1, 0
	v_lshl_add_u64 v[12:13], s[0:1], 0, v[0:1]
	global_load_dwordx4 v[32:35], v[12:13], off
	v_lshl_add_u64 v[12:13], s[34:35], 2, v[12:13]
	global_load_dwordx4 v[36:39], v[12:13], off
	v_lshlrev_b32_e32 v1, 2, v7
	v_mul_u32_u24_e32 v7, 0x104, v10
	v_add3_u32 v44, 0, v7, v1
	s_waitcnt vmcnt(2)
	v_pk_mul_f32 v[24:25], v[24:25], v[20:21] op_sel_hi:[1,0]
	v_pk_mul_f32 v[26:27], v[26:27], v[20:21] op_sel_hi:[1,0]
	v_pk_mul_f32 v[28:29], v[28:29], v[22:23] op_sel_hi:[1,0]
	v_pk_mul_f32 v[30:31], v[30:31], v[22:23] op_sel_hi:[1,0]
	v_cvt_pk_bf16_f32 v0, v24, v28
	v_cvt_pk_bf16_f32 v1, v25, v29
	v_cvt_pk_bf16_f32 v2, v26, v30
	v_cvt_pk_bf16_f32 v4, v27, v31
	ds_write2_b32 v44, v0, v1 offset1:65
	ds_write2_b32 v44, v2, v4 offset0:130 offset1:195
	s_waitcnt vmcnt(0)
	v_pk_mul_f32 v[32:33], v[32:33], v[40:41] op_sel_hi:[1,0]
	v_pk_mul_f32 v[34:35], v[34:35], v[40:41] op_sel_hi:[1,0]
	v_pk_mul_f32 v[36:37], v[36:37], v[42:43] op_sel_hi:[1,0]
	v_pk_mul_f32 v[38:39], v[38:39], v[42:43] op_sel_hi:[1,0]
	v_cvt_pk_bf16_f32 v0, v32, v36
	v_cvt_pk_bf16_f32 v1, v33, v37
	v_cvt_pk_bf16_f32 v2, v34, v38
	v_cvt_pk_bf16_f32 v4, v35, v39
	ds_write2_b32 v44, v0, v1 offset0:32 offset1:97
	ds_write2_b32 v44, v2, v4 offset0:162 offset1:227
	s_branch .LBB0_17

.LBB0_380:
	v_readlane_b32 s0, v242, 8
	v_readlane_b32 s1, v242, 9
	s_nop 0
	s_add_i32 s19, s19, s0

.LBB0_434:
	s_lshl_b32 s10, s15, 7
	s_waitcnt lgkmcnt(0)
	v_ashrrev_i32_e32 v7, 4, v3
	v_lshl_add_u32 v4, v7, 1, s10
	v_ashrrev_i32_e32 v5, 31, v4
	v_mov_b32_e32 v20, 1.0
	v_mov_b32_e32 v22, 1.0
	v_mov_b32_e32 v40, 1.0
	v_mov_b32_e32 v42, 1.0
	s_cmp_eq_u64 s[8:9], 0
	s_cbranch_scc1 .Lwt_nogain
	v_lshl_add_u64 v[0:1], v[4:5], 2, s[8:9]
	global_load_dword v20, v[0:1], off
	global_load_dword v22, v[0:1], off offset:4
	global_load_dword v40, v[0:1], off offset:256
	global_load_dword v42, v[0:1], off offset:260
.Lwt_nogain:
	s_ashr_i32 s13, s12, 31
	v_lshlrev_b32_e32 v0, 2, v3
	s_lshl_b64 s[12:13], s[12:13], 2
	v_and_b32_e32 v8, 60, v0
	s_add_u32 s6, s6, s12
	s_addc_u32 s7, s7, s13
	v_lshlrev_b32_e32 v136, 2, v8
	v_lshl_add_u64 v[0:1], s[6:7], 0, v[136:137]
	v_mul_u32_u24_e32 v16, 0x104, v8
	v_mad_u64_u32 v[8:9], s[6:7], v4, s34, 0
	v_mov_b32_e32 v4, v9
	v_mad_u64_u32 v[4:5], s[6:7], v5, s34, v[4:5]
	v_mov_b32_e32 v9, v4
	v_lshl_add_u64 v[4:5], v[8:9], 2, v[0:1]
	global_load_dwordx4 v[24:27], v[4:5], off
	v_lshl_add_u64 v[10:11], s[34:35], 2, v[4:5]
	global_load_dwordx4 v[28:31], v[10:11], off
	s_lshl_b32 s0, s34, 8
	s_mov_b32 s1, 0
	v_lshl_add_u64 v[12:13], s[0:1], 0, v[4:5]
	global_load_dwordx4 v[32:35], v[12:13], off
	v_lshl_add_u64 v[12:13], s[34:35], 2, v[12:13]
	global_load_dwordx4 v[36:39], v[12:13], off
	v_lshlrev_b32_e32 v6, 2, v7
	v_add3_u32 v9, 0, v16, v6
	s_waitcnt vmcnt(2)
	v_pk_mul_f32 v[24:25], v[24:25], v[20:21] op_sel_hi:[1,0]
	v_pk_mul_f32 v[26:27], v[26:27], v[20:21] op_sel_hi:[1,0]
	v_pk_mul_f32 v[28:29], v[28:29], v[22:23] op_sel_hi:[1,0]
	v_pk_mul_f32 v[30:31], v[30:31], v[22:23] op_sel_hi:[1,0]
	v_cvt_pk_bf16_f32 v0, v24, v28
	v_cvt_pk_bf16_f32 v1, v25, v29
	v_cvt_pk_bf16_f32 v2, v26, v30
	v_cvt_pk_bf16_f32 v4, v27, v31
	ds_write2_b32 v9, v0, v1 offset1:65
	ds_write2_b32 v9, v2, v4 offset0:130 offset1:195
	s_waitcnt vmcnt(0)
	v_pk_mul_f32 v[32:33], v[32:33], v[40:41] op_sel_hi:[1,0]
	v_pk_mul_f32 v[34:35], v[34:35], v[40:41] op_sel_hi:[1,0]
	v_pk_mul_f32 v[36:37], v[36:37], v[42:43] op_sel_hi:[1,0]
	v_pk_mul_f32 v[38:39], v[38:39], v[42:43] op_sel_hi:[1,0]
	v_cvt_pk_bf16_f32 v0, v32, v36
	v_cvt_pk_bf16_f32 v1, v33, v37
	v_cvt_pk_bf16_f32 v2, v34, v38
	v_cvt_pk_bf16_f32 v4, v35, v39
	ds_write2_b32 v9, v0, v1 offset0:32 offset1:97
	ds_write2_b32 v9, v2, v4 offset0:162 offset1:227
	v_ashrrev_i32_e32 v8, 3, v3
	v_lshlrev_b32_e32 v1, 5, v3
	v_mul_lo_u32 v0, v8, s76
	v_and_b32_e32 v136, 0xe0, v1
	v_add_u32_e32 v8, s11, v8
	v_add3_u32 v6, 0, v0, v136
	v_ashrrev_i32_e32 v9, 31, v8
	s_waitcnt lgkmcnt(0)
	s_barrier
	ds_read2_b32 v[0:1], v6 offset1:1
	ds_read2_b32 v[2:3], v6 offset0:2 offset1:3
	ds_read2_b32 v[4:5], v6 offset0:4 offset1:5
	ds_read2_b32 v[6:7], v6 offset0:6 offset1:7
	v_mul_lo_u32 v10, s4, v9
	v_mul_lo_u32 v11, s5, v8
	v_mad_u64_u32 v[8:9], s[0:1], s4, v8, 0
	v_add3_u32 v9, v9, v10, v11
	v_lshl_add_u64 v[8:9], v[8:9], 1, s[2:3]
	s_ashr_i32 s11, s10, 31
	v_lshl_add_u64 v[8:9], s[10:11], 1, v[8:9]
	v_lshl_add_u64 v[8:9], v[8:9], 0, v[136:137]
	s_waitcnt lgkmcnt(2)
	global_store_dwordx4 v[8:9], v[0:3], off
	s_waitcnt lgkmcnt(0)
	global_store_dwordx4 v[8:9], v[4:7], off offset:16
	s_barrier
	s_branch .LBB0_380

.LBB0_561:
	v_readlane_b32 s0, v242, 8
	v_readlane_b32 s1, v242, 9
	s_nop 0
	s_add_i32 s17, s17, s0
	s_cmp_lt_i32 s17, s16
	s_cbranch_scc0 .LBB0_445
